# conv weight loads issued after the item's input loads (counted wait) so they no longer queue ahead of the critical loads
# speedup vs baseline: 1.0069x; 1.0018x over previous
; DI void conv_item(LAS unsigned char* lds, int item, const bf16_t* P, const float* cw, const float* cb, const float* lng, const float* lnb, bf16_t* MIX) {
;     ...
;     const int c = tid & 127, tq = tid >> 7;
;     float y[32];
;     {
;         float w[31];
; #pragma unroll
;         for (int k = 0; k < 31; ++k) w[k] = cw[k * 1024 + cbase + c];
;         const float bias = cb[cbase + c];
.LBB0_528:
	s_or_b64 exec, exec, s[26:27]
	v_lshlrev_b32_e32 v250, 3, v252
	v_lshl_add_u32 v250, s37, 2, v250
	global_load_dwordx2 v[126:127], v250, s[14:15]
	s_add_u32 vcc_lo, s14, 0x1000
	s_addc_u32 vcc_hi, s15, 0
	global_load_dwordx2 v[128:129], v250, vcc
	s_add_u32 vcc_lo, s14, 0x2000
	s_addc_u32 vcc_hi, s15, 0
	global_load_dwordx2 v[130:131], v250, vcc
	s_add_u32 vcc_lo, s14, 0x3000
	s_addc_u32 vcc_hi, s15, 0
	global_load_dwordx2 v[132:133], v250, vcc
	s_add_u32 vcc_lo, s14, 0x4000
	s_addc_u32 vcc_hi, s15, 0
	global_load_dwordx2 v[134:135], v250, vcc
	s_add_u32 vcc_lo, s14, 0x5000
	s_addc_u32 vcc_hi, s15, 0
	global_load_dwordx2 v[136:137], v250, vcc
	s_add_u32 vcc_lo, s14, 0x6000
	s_addc_u32 vcc_hi, s15, 0
	global_load_dwordx2 v[138:139], v250, vcc
	s_add_u32 vcc_lo, s14, 0x7000
	s_addc_u32 vcc_hi, s15, 0
	global_load_dwordx2 v[140:141], v250, vcc
	s_add_u32 vcc_lo, s14, 0x8000
	s_addc_u32 vcc_hi, s15, 0
	global_load_dwordx2 v[142:143], v250, vcc
	s_add_u32 vcc_lo, s14, 0x9000
	s_addc_u32 vcc_hi, s15, 0
	global_load_dwordx2 v[144:145], v250, vcc
	s_add_u32 vcc_lo, s14, 0xa000
	s_addc_u32 vcc_hi, s15, 0
	global_load_dwordx2 v[146:147], v250, vcc
	s_add_u32 vcc_lo, s14, 0xb000
	s_addc_u32 vcc_hi, s15, 0
	global_load_dwordx2 v[148:149], v250, vcc
	s_add_u32 vcc_lo, s14, 0xc000
	s_addc_u32 vcc_hi, s15, 0
	global_load_dwordx2 v[150:151], v250, vcc
	s_add_u32 vcc_lo, s14, 0xd000
	s_addc_u32 vcc_hi, s15, 0
	global_load_dwordx2 v[152:153], v250, vcc
	s_add_u32 vcc_lo, s14, 0xe000
	s_addc_u32 vcc_hi, s15, 0
	global_load_dwordx2 v[154:155], v250, vcc
	s_add_u32 vcc_lo, s14, 0xf000
	s_addc_u32 vcc_hi, s15, 0
	global_load_dwordx2 v[156:157], v250, vcc
	s_add_u32 vcc_lo, s14, 0x10000
	s_addc_u32 vcc_hi, s15, 0
	global_load_dwordx2 v[158:159], v250, vcc
	s_add_u32 vcc_lo, s14, 0x11000
	s_addc_u32 vcc_hi, s15, 0
	global_load_dwordx2 v[160:161], v250, vcc
	s_add_u32 vcc_lo, s14, 0x12000
	s_addc_u32 vcc_hi, s15, 0
	global_load_dwordx2 v[162:163], v250, vcc
	s_add_u32 vcc_lo, s14, 0x13000
	s_addc_u32 vcc_hi, s15, 0
	global_load_dwordx2 v[164:165], v250, vcc
	s_add_u32 vcc_lo, s14, 0x14000
	s_addc_u32 vcc_hi, s15, 0
	global_load_dwordx2 v[166:167], v250, vcc
	s_add_u32 vcc_lo, s14, 0x15000
	s_addc_u32 vcc_hi, s15, 0
	global_load_dwordx2 v[168:169], v250, vcc
	s_add_u32 vcc_lo, s14, 0x16000
	s_addc_u32 vcc_hi, s15, 0
	global_load_dwordx2 v[170:171], v250, vcc
	s_add_u32 vcc_lo, s14, 0x17000
	s_addc_u32 vcc_hi, s15, 0
	global_load_dwordx2 v[172:173], v250, vcc
	s_add_u32 vcc_lo, s14, 0x18000
	s_addc_u32 vcc_hi, s15, 0
	global_load_dwordx2 v[174:175], v250, vcc
	s_add_u32 vcc_lo, s14, 0x19000
	s_addc_u32 vcc_hi, s15, 0
	global_load_dwordx2 v[176:177], v250, vcc
	s_add_u32 vcc_lo, s14, 0x1a000
	s_addc_u32 vcc_hi, s15, 0
	global_load_dwordx2 v[178:179], v250, vcc
	s_add_u32 vcc_lo, s14, 0x1b000
	s_addc_u32 vcc_hi, s15, 0
	global_load_dwordx2 v[180:181], v250, vcc
	s_add_u32 vcc_lo, s14, 0x1c000
	s_addc_u32 vcc_hi, s15, 0
	global_load_dwordx2 v[182:183], v250, vcc
	s_add_u32 vcc_lo, s14, 0x1d000
	s_addc_u32 vcc_hi, s15, 0
	global_load_dwordx2 v[184:185], v250, vcc
	s_add_u32 vcc_lo, s14, 0x1e000
	s_addc_u32 vcc_hi, s15, 0
	global_load_dwordx2 v[186:187], v250, vcc
	global_load_dwordx2 v[188:189], v250, s[16:17]
	s_waitcnt vmcnt(32)
; #define LAS __attribute__((address_space(3)))
; DI float sigmoidf_(float x) { return frcp(1.f + fexp(-x)); }
; DI void conv_item(LAS unsigned char* lds, int item, const bf16_t* P, const float* cw, const float* cb, const float* lng, const float* lnb, bf16_t* MIX) {
;     ...
; #pragma unroll
;         for (int j = 0; j < 5; ++j) {
;             const int id = tid + 512 * j, row = id >> 4, c8 = (id & 15) * 8;
;             const u32x4 v = vv[j], gg = gv[j];
;             f32x4 u0, u1;
;             u0[0] = bflo(v.x) * sigmoidf_(bflo(gg.x)); u0[1] = bfhi(v.x) * sigmoidf_(bfhi(gg.x));
;             u0[2] = bflo(v.y) * sigmoidf_(bflo(gg.y)); u0[3] = bfhi(v.y) * sigmoidf_(bfhi(gg.y));
;             u1[0] = bflo(v.z) * sigmoidf_(bflo(gg.z)); u1[1] = bfhi(v.z) * sigmoidf_(bfhi(gg.z));
;             u1[2] = bflo(v.w) * sigmoidf_(bflo(gg.w)); u1[3] = bfhi(v.w) * sigmoidf_(bfhi(gg.w));
;             if (id < 158 * 16) { *(LAS f32x4*)(U + row * 128 + c8) = u0; *(LAS f32x4*)(U + row * 128 + c8 + 4) = u1; }
;         }
	v_and_b32_e32 v40, 0xffff0000, v39
	v_lshlrev_b32_e32 v39, 16, v39
	v_mul_f32_e32 v40, 0xbfb8aa3b, v40
	v_mul_f32_e32 v39, 0xbfb8aa3b, v39
	v_exp_f32_e32 v40, v40
	v_exp_f32_e32 v47, v39
	v_add_f32_e32 v39, 1.0, v40
	v_add_f32_e32 v40, 1.0, v47
	v_and_b32_e32 v47, 0xffff0000, v38
	v_mul_f32_e32 v47, 0xbfb8aa3b, v47
	v_exp_f32_e32 v47, v47
	v_lshlrev_b32_e32 v38, 16, v38
	v_mul_f32_e32 v38, 0xbfb8aa3b, v38
	v_exp_f32_e32 v49, v38
	v_rcp_f32_e32 v38, v40
	v_add_f32_e32 v40, 1.0, v47
	v_and_b32_e32 v47, 0xffff0000, v37
	v_mul_f32_e32 v47, 0xbfb8aa3b, v47
	v_exp_f32_e32 v47, v47
	v_rcp_f32_e32 v51, v40
	v_add_f32_e32 v40, 1.0, v49
	v_lshlrev_b32_e32 v37, 16, v37
	v_mul_f32_e32 v37, 0xbfb8aa3b, v37
	v_rcp_f32_e32 v50, v40
	v_add_f32_e32 v40, 1.0, v47
	v_exp_f32_e32 v37, v37
	v_rcp_f32_e32 v53, v40
	v_and_b32_e32 v40, 0xffff0000, v36
	v_lshlrev_b32_e32 v36, 16, v36
	v_mul_f32_e32 v40, 0xbfb8aa3b, v40
	v_mul_f32_e32 v36, 0xbfb8aa3b, v36
	v_exp_f32_e32 v40, v40
	v_exp_f32_e32 v36, v36
	v_rcp_f32_e32 v39, v39
	v_add_f32_e32 v37, 1.0, v37
	v_rcp_f32_e32 v52, v37
	v_add_f32_e32 v37, 1.0, v40
	v_add_f32_e32 v36, 1.0, v36
	v_rcp_f32_e32 v55, v37
	v_rcp_f32_e32 v54, v36
	v_lshlrev_b32_e32 v36, 16, v34
	v_and_b32_e32 v37, 0xffff0000, v34
	v_lshlrev_b32_e32 v34, 16, v35
	v_and_b32_e32 v35, 0xffff0000, v35
	v_pk_mul_f32 v[38:39], v[38:39], v[34:35]
	v_lshlrev_b32_e32 v34, 16, v32
	v_and_b32_e32 v35, 0xffff0000, v32
	v_lshlrev_b32_e32 v32, 16, v33
	v_and_b32_e32 v33, 0xffff0000, v33
	v_pk_mul_f32 v[52:53], v[52:53], v[32:33]
	v_and_b32_e32 v32, 0xffff0000, v31
	v_lshlrev_b32_e32 v31, 16, v31
	v_mul_f32_e32 v32, 0xbfb8aa3b, v32
	v_mul_f32_e32 v31, 0xbfb8aa3b, v31
	v_exp_f32_e32 v32, v32
	v_exp_f32_e32 v33, v31
	v_pk_mul_f32 v[36:37], v[50:51], v[36:37]
	v_pk_mul_f32 v[50:51], v[54:55], v[34:35]
	v_add_f32_e32 v31, 1.0, v32
	v_add_f32_e32 v32, 1.0, v33
	v_and_b32_e32 v33, 0xffff0000, v30
	v_mul_f32_e32 v33, 0xbfb8aa3b, v33
	v_lshlrev_b32_e32 v30, 16, v30
	v_exp_f32_e32 v33, v33
	v_mul_f32_e32 v30, 0xbfb8aa3b, v30
	v_exp_f32_e32 v34, v30
	v_rcp_f32_e32 v30, v32
	v_add_f32_e32 v32, 1.0, v33
	v_rcp_f32_e32 v33, v32
	v_add_f32_e32 v32, 1.0, v34
	v_and_b32_e32 v34, 0xffff0000, v29
	v_mul_f32_e32 v34, 0xbfb8aa3b, v34
	v_exp_f32_e32 v34, v34
	v_lshlrev_b32_e32 v29, 16, v29
	v_mul_f32_e32 v29, 0xbfb8aa3b, v29
	v_exp_f32_e32 v29, v29
	v_add_f32_e32 v34, 1.0, v34
	v_rcp_f32_e32 v35, v34
	v_and_b32_e32 v34, 0xffff0000, v28
	v_lshlrev_b32_e32 v28, 16, v28
	v_mul_f32_e32 v34, 0xbfb8aa3b, v34
	v_mul_f32_e32 v28, 0xbfb8aa3b, v28
	ds_write_b128 v73, v[36:39] offset:16
	v_exp_f32_e32 v36, v34
	v_exp_f32_e32 v28, v28
	v_rcp_f32_e32 v31, v31
	v_add_f32_e32 v29, 1.0, v29
	v_rcp_f32_e32 v34, v29
	v_add_f32_e32 v29, 1.0, v36
	v_add_f32_e32 v28, 1.0, v28
	v_rcp_f32_e32 v37, v29
	v_rcp_f32_e32 v36, v28
	v_lshlrev_b32_e32 v28, 16, v26
	v_and_b32_e32 v29, 0xffff0000, v26
	v_lshlrev_b32_e32 v26, 16, v27
	v_and_b32_e32 v27, 0xffff0000, v27
	v_pk_mul_f32 v[30:31], v[30:31], v[26:27]
	v_lshlrev_b32_e32 v26, 16, v24
	v_and_b32_e32 v27, 0xffff0000, v24
	v_lshlrev_b32_e32 v24, 16, v25
	v_and_b32_e32 v25, 0xffff0000, v25
	v_pk_mul_f32 v[34:35], v[34:35], v[24:25]
	v_and_b32_e32 v24, 0xffff0000, v15
	v_lshlrev_b32_e32 v15, 16, v15
	v_mul_f32_e32 v24, 0xbfb8aa3b, v24
	v_mul_f32_e32 v15, 0xbfb8aa3b, v15
	v_exp_f32_e32 v24, v24
	v_exp_f32_e32 v25, v15
	v_rcp_f32_e32 v32, v32
	ds_write_b128 v73, v[50:53]
	v_add_f32_e32 v15, 1.0, v24
	v_add_f32_e32 v24, 1.0, v25
	v_and_b32_e32 v25, 0xffff0000, v14
	v_mul_f32_e32 v25, 0xbfb8aa3b, v25
	v_lshlrev_b32_e32 v14, 16, v14
	v_exp_f32_e32 v25, v25
	v_mul_f32_e32 v14, 0xbfb8aa3b, v14
	v_pk_mul_f32 v[28:29], v[32:33], v[28:29]
	v_pk_mul_f32 v[32:33], v[36:37], v[26:27]
	v_exp_f32_e32 v26, v14
	v_rcp_f32_e32 v14, v24
	v_add_f32_e32 v24, 1.0, v25
	v_rcp_f32_e32 v25, v24
	v_add_f32_e32 v24, 1.0, v26
	v_and_b32_e32 v26, 0xffff0000, v13
	v_mul_f32_e32 v26, 0xbfb8aa3b, v26
	v_exp_f32_e32 v26, v26
	v_lshlrev_b32_e32 v13, 16, v13
	v_mul_f32_e32 v13, 0xbfb8aa3b, v13
	v_exp_f32_e32 v13, v13
	v_add_f32_e32 v26, 1.0, v26
	v_rcp_f32_e32 v27, v26
	v_and_b32_e32 v26, 0xffff0000, v12
	v_lshlrev_b32_e32 v12, 16, v12
	v_mul_f32_e32 v26, 0xbfb8aa3b, v26
	v_mul_f32_e32 v12, 0xbfb8aa3b, v12
	ds_write_b128 v74, v[28:31] offset:16
	v_exp_f32_e32 v28, v26
	v_exp_f32_e32 v12, v12
	v_add_f32_e32 v13, 1.0, v13
	v_rcp_f32_e32 v15, v15
	v_rcp_f32_e32 v26, v13
	v_add_f32_e32 v13, 1.0, v28
	v_add_f32_e32 v12, 1.0, v12
	v_rcp_f32_e32 v24, v24
	v_rcp_f32_e32 v29, v13
	v_rcp_f32_e32 v28, v12
	v_lshlrev_b32_e32 v12, 16, v22
	v_and_b32_e32 v13, 0xffff0000, v22
	v_lshlrev_b32_e32 v22, 16, v23
	v_and_b32_e32 v23, 0xffff0000, v23
	v_pk_mul_f32 v[14:15], v[14:15], v[22:23]
	v_lshlrev_b32_e32 v22, 16, v20
	v_and_b32_e32 v23, 0xffff0000, v20
	v_lshlrev_b32_e32 v20, 16, v21
	v_and_b32_e32 v21, 0xffff0000, v21
	v_pk_mul_f32 v[12:13], v[24:25], v[12:13]
	v_pk_mul_f32 v[22:23], v[28:29], v[22:23]
	v_pk_mul_f32 v[24:25], v[26:27], v[20:21]
	ds_write_b128 v74, v[32:35]
	ds_write_b128 v75, v[22:25]
	ds_write_b128 v75, v[12:15] offset:16
	s_and_saveexec_b64 s[26:27], s[4:5]
	s_cbranch_execz .LBB0_530
	v_and_b32_e32 v12, 0xffff0000, v19
	v_mul_f32_e32 v12, 0xbfb8aa3b, v12
	v_lshlrev_b32_e32 v13, 16, v19
	v_exp_f32_e32 v12, v12
	v_mul_f32_e32 v13, 0xbfb8aa3b, v13
	v_exp_f32_e32 v13, v13
	v_lshlrev_b32_e32 v14, 16, v18
	v_add_f32_e32 v12, 1.0, v12
	v_rcp_f32_e32 v15, v12
	v_add_f32_e32 v12, 1.0, v13
	v_and_b32_e32 v13, 0xffff0000, v18
	v_mul_f32_e32 v13, 0xbfb8aa3b, v13
	v_exp_f32_e32 v13, v13
	v_mul_f32_e32 v14, 0xbfb8aa3b, v14
	v_exp_f32_e32 v18, v14
	v_rcp_f32_e32 v14, v12
	v_add_f32_e32 v12, 1.0, v13
	v_rcp_f32_e32 v13, v12
	v_add_f32_e32 v12, 1.0, v18
	v_and_b32_e32 v18, 0xffff0000, v17
	v_mul_f32_e32 v18, 0xbfb8aa3b, v18
	v_exp_f32_e32 v18, v18
	v_lshlrev_b32_e32 v17, 16, v17
	v_mul_f32_e32 v17, 0xbfb8aa3b, v17
	v_exp_f32_e32 v17, v17
	v_add_f32_e32 v18, 1.0, v18
	v_rcp_f32_e32 v19, v18
	v_and_b32_e32 v18, 0xffff0000, v16
	v_lshlrev_b32_e32 v16, 16, v16
	v_mul_f32_e32 v18, 0xbfb8aa3b, v18
	v_mul_f32_e32 v16, 0xbfb8aa3b, v16
	v_exp_f32_e32 v20, v18
	v_exp_f32_e32 v16, v16
	v_add_f32_e32 v17, 1.0, v17
	v_rcp_f32_e32 v18, v17
	v_add_f32_e32 v17, 1.0, v20
	v_add_f32_e32 v16, 1.0, v16
	v_rcp_f32_e32 v17, v17
	v_rcp_f32_e32 v16, v16
	v_rcp_f32_e32 v12, v12
	v_lshlrev_b32_e32 v20, 16, v10
	v_and_b32_e32 v21, 0xffff0000, v10
	v_lshlrev_b32_e32 v10, 16, v11
	v_and_b32_e32 v11, 0xffff0000, v11
	v_pk_mul_f32 v[14:15], v[14:15], v[10:11]
	v_lshlrev_b32_e32 v10, 16, v8
	v_and_b32_e32 v11, 0xffff0000, v8
	v_lshlrev_b32_e32 v8, 16, v9
	v_and_b32_e32 v9, 0xffff0000, v9
	v_pk_mul_f32 v[16:17], v[16:17], v[10:11]
	v_pk_mul_f32 v[18:19], v[18:19], v[8:9]
	v_pk_mul_f32 v[12:13], v[12:13], v[20:21]
	ds_write_b128 v76, v[16:19]
	ds_write_b128 v76, v[12:15] offset:16
